# v23 + GEMM K loops: the mid-segment priority yield sits after 8 of the 32 MFMAs instead of after 16
# baseline (speedup 1.0000x reference)
.LBB0_348:
	s_add_u32 s40, s22, 0xfffc0080
	s_addc_u32 s41, s23, -1
	s_add_i32 s71, 0, 0x10000
	s_cmp_eq_u32 s70, 12
	s_cselect_b32 s57, s14, s41
	s_cselect_b32 s56, s33, s40
	s_cselect_b32 s41, s27, s69
	s_cselect_b32 s40, s36, s49
	s_add_i32 s76, 0, 0x14000
	s_waitcnt lgkmcnt(0)
	v_add_u32_e32 v76, s71, v235
	v_add_u32_e32 v100, s76, v235
	ds_read_b128 v[64:67], v76
	ds_read_b128 v[68:71], v76 offset:1024
	ds_read_b128 v[72:75], v76 offset:2048
	ds_read_b128 v[76:79], v76 offset:3072
	ds_read_b128 v[84:87], v100
	ds_read_b128 v[88:91], v100 offset:1024
	ds_read_b128 v[96:99], v100 offset:2048
	ds_read_b128 v[100:103], v100 offset:3072
	v_lshl_add_u64 v[208:209], s[22:23], 0, v[202:203]
	s_add_i32 m0, s55, 0xc000
	ds_read_b128 v[160:163], v239
	ds_read_b128 v[164:167], v239 offset:1024
	ds_read_b128 v[168:171], v239 offset:2048
	ds_read_b128 v[172:175], v239 offset:3072
	ds_read_b128 v[176:179], v239 offset:4096
	ds_read_b128 v[180:183], v239 offset:5120
	ds_read_b128 v[184:187], v239 offset:6144
	ds_read_b128 v[204:207], v239 offset:7168
	global_load_lds_dwordx4 v[208:209], off
	v_lshl_add_u64 v[208:209], s[22:23], 0, v[200:201]
	s_add_i32 m0, s55, 0xe000
	s_nop 0
	global_load_lds_dwordx4 v[208:209], off
	s_waitcnt vmcnt(8)
	s_waitcnt lgkmcnt(0)
	s_barrier
	s_setprio 1
	s_waitcnt lgkmcnt(0)
	v_mfma_f32_16x16x32_bf16 v[156:159], v[64:67], v[160:163], v[156:159]
	v_mfma_f32_16x16x32_bf16 v[152:155], v[72:75], v[160:163], v[152:155]
	v_mfma_f32_16x16x32_bf16 v[140:143], v[64:67], v[168:171], v[140:143]
	v_mfma_f32_16x16x32_bf16 v[136:139], v[72:75], v[168:171], v[136:139]
	v_mfma_f32_16x16x32_bf16 v[124:127], v[64:67], v[176:179], v[124:127]
	v_mfma_f32_16x16x32_bf16 v[120:123], v[72:75], v[176:179], v[120:123]
	v_mfma_f32_16x16x32_bf16 v[108:111], v[64:67], v[184:187], v[108:111]
	v_mfma_f32_16x16x32_bf16 v[104:107], v[72:75], v[184:187], v[104:107]
	s_setprio 0
	s_setprio 1
	v_mfma_f32_16x16x32_bf16 v[156:159], v[68:71], v[164:167], v[156:159]
	v_mfma_f32_16x16x32_bf16 v[152:155], v[76:79], v[164:167], v[152:155]
	v_mfma_f32_16x16x32_bf16 v[140:143], v[68:71], v[172:175], v[140:143]
	v_mfma_f32_16x16x32_bf16 v[136:139], v[76:79], v[172:175], v[136:139]
	v_mfma_f32_16x16x32_bf16 v[124:127], v[68:71], v[180:183], v[124:127]
	v_mfma_f32_16x16x32_bf16 v[120:123], v[76:79], v[180:183], v[120:123]
	v_mfma_f32_16x16x32_bf16 v[108:111], v[68:71], v[204:207], v[108:111]
	v_mfma_f32_16x16x32_bf16 v[104:107], v[76:79], v[204:207], v[104:107]
	v_mfma_f32_16x16x32_bf16 v[148:151], v[84:87], v[160:163], v[148:151]
	v_mfma_f32_16x16x32_bf16 v[144:147], v[96:99], v[160:163], v[144:147]
	v_mfma_f32_16x16x32_bf16 v[132:135], v[84:87], v[168:171], v[132:135]
	v_mfma_f32_16x16x32_bf16 v[128:131], v[96:99], v[168:171], v[128:131]
	v_mfma_f32_16x16x32_bf16 v[116:119], v[84:87], v[176:179], v[116:119]
	v_mfma_f32_16x16x32_bf16 v[112:115], v[96:99], v[176:179], v[112:115]
	v_mfma_f32_16x16x32_bf16 v[92:95], v[84:87], v[184:187], v[92:95]
	v_mfma_f32_16x16x32_bf16 v[80:83], v[96:99], v[184:187], v[80:83]
	v_mfma_f32_16x16x32_bf16 v[148:151], v[88:91], v[164:167], v[148:151]
	v_mfma_f32_16x16x32_bf16 v[144:147], v[100:103], v[164:167], v[144:147]
	v_mfma_f32_16x16x32_bf16 v[132:135], v[88:91], v[172:175], v[132:135]
	v_mfma_f32_16x16x32_bf16 v[128:131], v[100:103], v[172:175], v[128:131]
	v_mfma_f32_16x16x32_bf16 v[116:119], v[88:91], v[180:183], v[116:119]
	v_mfma_f32_16x16x32_bf16 v[112:115], v[100:103], v[180:183], v[112:115]
	v_mfma_f32_16x16x32_bf16 v[92:95], v[88:91], v[204:207], v[92:95]
	v_mfma_f32_16x16x32_bf16 v[80:83], v[100:103], v[204:207], v[80:83]
	s_setprio 0
	s_barrier
	s_add_i32 s71, s71, s37
	v_lshl_add_u64 v[208:209], s[40:41], 0, v[188:189]
	s_mov_b32 m0, s71
	ds_read_b128 v[160:163], v239 offset:16384
	ds_read_b128 v[164:167], v239 offset:17408
	ds_read_b128 v[168:171], v239 offset:18432
	ds_read_b128 v[172:175], v239 offset:19456
	ds_read_b128 v[176:179], v239 offset:20480
	ds_read_b128 v[180:183], v239 offset:21504
	ds_read_b128 v[184:187], v239 offset:22528
	ds_read_b128 v[204:207], v239 offset:23552
	global_load_lds_dwordx4 v[208:209], off
	s_add_i32 m0, s71, 0x2000
	s_add_u32 s72, s40, 0x40000
	v_lshl_add_u64 v[210:211], s[40:41], 0, v[198:199]
	s_addc_u32 s73, s41, 0
	s_add_i32 s71, s76, s37
	global_load_lds_dwordx4 v[210:211], off
	v_lshl_add_u64 v[212:213], s[72:73], 0, v[188:189]
	s_mov_b32 m0, s71
	v_lshl_add_u64 v[214:215], s[56:57], 0, v[196:197]
	global_load_lds_dwordx4 v[212:213], off
	v_lshl_add_u64 v[212:213], s[72:73], 0, v[198:199]
	s_add_i32 m0, s71, 0x2000
	s_nop 0
	global_load_lds_dwordx4 v[212:213], off
	v_lshl_add_u64 v[212:213], s[56:57], 0, v[194:195]
	s_mov_b32 m0, s55
	s_nop 0
	global_load_lds_dwordx4 v[212:213], off
	s_mov_b32 m0, s60
	s_nop 0
	global_load_lds_dwordx4 v[214:215], off
	s_waitcnt vmcnt(8)
	s_waitcnt lgkmcnt(0)
	s_barrier
	s_setprio 1
	s_waitcnt lgkmcnt(0)
	v_mfma_f32_16x16x32_bf16 v[60:63], v[64:67], v[160:163], v[60:63]
	v_mfma_f32_16x16x32_bf16 v[56:59], v[72:75], v[160:163], v[56:59]
	v_mfma_f32_16x16x32_bf16 v[44:47], v[64:67], v[168:171], v[44:47]
	v_mfma_f32_16x16x32_bf16 v[40:43], v[72:75], v[168:171], v[40:43]
	v_mfma_f32_16x16x32_bf16 v[28:31], v[64:67], v[176:179], v[28:31]
	v_mfma_f32_16x16x32_bf16 v[24:27], v[72:75], v[176:179], v[24:27]
	v_mfma_f32_16x16x32_bf16 v[12:15], v[64:67], v[184:187], v[12:15]
	v_mfma_f32_16x16x32_bf16 v[8:11], v[72:75], v[184:187], v[8:11]
	s_setprio 0
	s_setprio 1
	v_mfma_f32_16x16x32_bf16 v[60:63], v[68:71], v[164:167], v[60:63]
	v_mfma_f32_16x16x32_bf16 v[56:59], v[76:79], v[164:167], v[56:59]
	v_mfma_f32_16x16x32_bf16 v[44:47], v[68:71], v[172:175], v[44:47]
	v_mfma_f32_16x16x32_bf16 v[40:43], v[76:79], v[172:175], v[40:43]
	v_mfma_f32_16x16x32_bf16 v[28:31], v[68:71], v[180:183], v[28:31]
	v_mfma_f32_16x16x32_bf16 v[24:27], v[76:79], v[180:183], v[24:27]
	v_mfma_f32_16x16x32_bf16 v[12:15], v[68:71], v[204:207], v[12:15]
	v_mfma_f32_16x16x32_bf16 v[8:11], v[76:79], v[204:207], v[8:11]
	v_mfma_f32_16x16x32_bf16 v[52:55], v[84:87], v[160:163], v[52:55]
	v_mfma_f32_16x16x32_bf16 v[48:51], v[96:99], v[160:163], v[48:51]
	v_mfma_f32_16x16x32_bf16 v[36:39], v[84:87], v[168:171], v[36:39]
	v_mfma_f32_16x16x32_bf16 v[32:35], v[96:99], v[168:171], v[32:35]
	v_mfma_f32_16x16x32_bf16 v[20:23], v[84:87], v[176:179], v[20:23]
	v_mfma_f32_16x16x32_bf16 v[16:19], v[96:99], v[176:179], v[16:19]
	v_mfma_f32_16x16x32_bf16 v[4:7], v[84:87], v[184:187], v[4:7]
	v_mfma_f32_16x16x32_bf16 v[0:3], v[96:99], v[184:187], v[0:3]
	v_mfma_f32_16x16x32_bf16 v[52:55], v[88:91], v[164:167], v[52:55]
	v_mfma_f32_16x16x32_bf16 v[48:51], v[100:103], v[164:167], v[48:51]
	v_mfma_f32_16x16x32_bf16 v[36:39], v[88:91], v[172:175], v[36:39]
	v_mfma_f32_16x16x32_bf16 v[32:35], v[100:103], v[172:175], v[32:35]
	v_mfma_f32_16x16x32_bf16 v[20:23], v[88:91], v[180:183], v[20:23]
	v_mfma_f32_16x16x32_bf16 v[16:19], v[100:103], v[180:183], v[16:19]
	v_mfma_f32_16x16x32_bf16 v[4:7], v[88:91], v[204:207], v[4:7]
	v_mfma_f32_16x16x32_bf16 v[0:3], v[100:103], v[204:207], v[0:3]
	s_setprio 0
	s_barrier
	s_add_i32 s71, 0, 0x18000
	s_add_i32 s72, 0, 0x1c000
	v_add_u32_e32 v76, s71, v235
	v_add_u32_e32 v100, s72, v235
	ds_read_b128 v[64:67], v76
	ds_read_b128 v[68:71], v76 offset:1024
	ds_read_b128 v[72:75], v76 offset:2048
	ds_read_b128 v[76:79], v76 offset:3072
	ds_read_b128 v[84:87], v100
	ds_read_b128 v[88:91], v100 offset:1024
	ds_read_b128 v[96:99], v100 offset:2048
	ds_read_b128 v[100:103], v100 offset:3072
	s_add_u32 s56, s56, 0x40000
	s_addc_u32 s57, s57, 0
	s_mov_b32 m0, s61
	v_lshl_add_u64 v[216:217], s[56:57], 0, v[194:195]
	ds_read_b128 v[160:163], v239 offset:32768
	ds_read_b128 v[164:167], v239 offset:33792
	ds_read_b128 v[168:171], v239 offset:34816
	ds_read_b128 v[172:175], v239 offset:35840
	ds_read_b128 v[176:179], v239 offset:36864
	ds_read_b128 v[180:183], v239 offset:37888
	ds_read_b128 v[184:187], v239 offset:38912
	ds_read_b128 v[204:207], v239 offset:39936
	global_load_lds_dwordx4 v[216:217], off
	v_lshl_add_u64 v[216:217], s[56:57], 0, v[196:197]
	s_mov_b32 m0, s62
	s_nop 0
	global_load_lds_dwordx4 v[216:217], off
	s_waitcnt vmcnt(8)
	s_waitcnt lgkmcnt(0)
	s_barrier
	s_setprio 1
	s_waitcnt lgkmcnt(0)
	v_mfma_f32_16x16x32_bf16 v[156:159], v[64:67], v[160:163], v[156:159]
	v_mfma_f32_16x16x32_bf16 v[152:155], v[72:75], v[160:163], v[152:155]
	v_mfma_f32_16x16x32_bf16 v[140:143], v[64:67], v[168:171], v[140:143]
	v_mfma_f32_16x16x32_bf16 v[136:139], v[72:75], v[168:171], v[136:139]
	v_mfma_f32_16x16x32_bf16 v[124:127], v[64:67], v[176:179], v[124:127]
	v_mfma_f32_16x16x32_bf16 v[120:123], v[72:75], v[176:179], v[120:123]
	v_mfma_f32_16x16x32_bf16 v[108:111], v[64:67], v[184:187], v[108:111]
	v_mfma_f32_16x16x32_bf16 v[104:107], v[72:75], v[184:187], v[104:107]
	s_setprio 0
	s_setprio 1
	v_mfma_f32_16x16x32_bf16 v[156:159], v[68:71], v[164:167], v[156:159]
	v_mfma_f32_16x16x32_bf16 v[152:155], v[76:79], v[164:167], v[152:155]
	v_mfma_f32_16x16x32_bf16 v[140:143], v[68:71], v[172:175], v[140:143]
	v_mfma_f32_16x16x32_bf16 v[136:139], v[76:79], v[172:175], v[136:139]
	v_mfma_f32_16x16x32_bf16 v[124:127], v[68:71], v[180:183], v[124:127]
	v_mfma_f32_16x16x32_bf16 v[120:123], v[76:79], v[180:183], v[120:123]
	v_mfma_f32_16x16x32_bf16 v[108:111], v[68:71], v[204:207], v[108:111]
	v_mfma_f32_16x16x32_bf16 v[104:107], v[76:79], v[204:207], v[104:107]
	v_mfma_f32_16x16x32_bf16 v[148:151], v[84:87], v[160:163], v[148:151]
	v_mfma_f32_16x16x32_bf16 v[144:147], v[96:99], v[160:163], v[144:147]
	v_mfma_f32_16x16x32_bf16 v[132:135], v[84:87], v[168:171], v[132:135]
	v_mfma_f32_16x16x32_bf16 v[128:131], v[96:99], v[168:171], v[128:131]
	v_mfma_f32_16x16x32_bf16 v[116:119], v[84:87], v[176:179], v[116:119]
	v_mfma_f32_16x16x32_bf16 v[112:115], v[96:99], v[176:179], v[112:115]
	v_mfma_f32_16x16x32_bf16 v[92:95], v[84:87], v[184:187], v[92:95]
	v_mfma_f32_16x16x32_bf16 v[80:83], v[96:99], v[184:187], v[80:83]
	v_mfma_f32_16x16x32_bf16 v[148:151], v[88:91], v[164:167], v[148:151]
	v_mfma_f32_16x16x32_bf16 v[144:147], v[100:103], v[164:167], v[144:147]
	v_mfma_f32_16x16x32_bf16 v[132:135], v[88:91], v[172:175], v[132:135]
	v_mfma_f32_16x16x32_bf16 v[128:131], v[100:103], v[172:175], v[128:131]
	v_mfma_f32_16x16x32_bf16 v[116:119], v[88:91], v[180:183], v[116:119]
	v_mfma_f32_16x16x32_bf16 v[112:115], v[100:103], v[180:183], v[112:115]
	v_mfma_f32_16x16x32_bf16 v[92:95], v[88:91], v[204:207], v[92:95]
	v_mfma_f32_16x16x32_bf16 v[80:83], v[100:103], v[204:207], v[80:83]
	s_setprio 0
	s_barrier
	s_add_i32 s56, s71, s37
	v_lshl_add_u64 v[208:209], v[208:209], 0, s[30:31]
	s_mov_b32 m0, s56
	ds_read_b128 v[160:163], v239 offset:49152
	ds_read_b128 v[164:167], v239 offset:50176
	ds_read_b128 v[168:171], v239 offset:51200
	ds_read_b128 v[172:175], v239 offset:52224
	ds_read_b128 v[176:179], v239 offset:53248
	ds_read_b128 v[180:183], v239 offset:54272
	ds_read_b128 v[184:187], v239 offset:55296
	ds_read_b128 v[204:207], v239 offset:56320
	global_load_lds_dwordx4 v[208:209], off
	s_add_i32 m0, s56, 0x2000
	s_add_u32 s40, s40, 0x40080
	v_lshl_add_u64 v[208:209], v[210:211], 0, s[30:31]
	s_addc_u32 s41, s41, 0
	s_add_i32 s56, s72, s37
	global_load_lds_dwordx4 v[208:209], off
	v_lshl_add_u64 v[208:209], s[40:41], 0, v[188:189]
	s_mov_b32 m0, s56
	s_nop 0
	global_load_lds_dwordx4 v[208:209], off
	v_lshl_add_u64 v[208:209], s[40:41], 0, v[198:199]
	s_add_i32 m0, s56, 0x2000
	s_nop 0
	global_load_lds_dwordx4 v[208:209], off
	v_lshl_add_u64 v[208:209], v[212:213], 0, s[30:31]
	s_mov_b32 m0, s64
	s_nop 0
	global_load_lds_dwordx4 v[208:209], off
	v_lshl_add_u64 v[208:209], v[214:215], 0, s[30:31]
	s_mov_b32 m0, s65
	s_nop 0
	global_load_lds_dwordx4 v[208:209], off
	s_waitcnt vmcnt(8)
	s_waitcnt lgkmcnt(0)
	s_barrier
	s_setprio 1
	s_waitcnt lgkmcnt(0)
	v_mfma_f32_16x16x32_bf16 v[60:63], v[64:67], v[160:163], v[60:63]
	v_mfma_f32_16x16x32_bf16 v[56:59], v[72:75], v[160:163], v[56:59]
	v_mfma_f32_16x16x32_bf16 v[44:47], v[64:67], v[168:171], v[44:47]
	v_mfma_f32_16x16x32_bf16 v[40:43], v[72:75], v[168:171], v[40:43]
	v_mfma_f32_16x16x32_bf16 v[28:31], v[64:67], v[176:179], v[28:31]
	v_mfma_f32_16x16x32_bf16 v[24:27], v[72:75], v[176:179], v[24:27]
	v_mfma_f32_16x16x32_bf16 v[12:15], v[64:67], v[184:187], v[12:15]
	v_mfma_f32_16x16x32_bf16 v[8:11], v[72:75], v[184:187], v[8:11]
	s_setprio 0
	s_setprio 1
	v_mfma_f32_16x16x32_bf16 v[60:63], v[68:71], v[164:167], v[60:63]
	v_mfma_f32_16x16x32_bf16 v[56:59], v[76:79], v[164:167], v[56:59]
	v_mfma_f32_16x16x32_bf16 v[44:47], v[68:71], v[172:175], v[44:47]
	v_mfma_f32_16x16x32_bf16 v[40:43], v[76:79], v[172:175], v[40:43]
	v_mfma_f32_16x16x32_bf16 v[28:31], v[68:71], v[180:183], v[28:31]
	v_mfma_f32_16x16x32_bf16 v[24:27], v[76:79], v[180:183], v[24:27]
	v_mfma_f32_16x16x32_bf16 v[12:15], v[68:71], v[204:207], v[12:15]
	v_mfma_f32_16x16x32_bf16 v[8:11], v[76:79], v[204:207], v[8:11]
	v_mfma_f32_16x16x32_bf16 v[52:55], v[84:87], v[160:163], v[52:55]
	v_mfma_f32_16x16x32_bf16 v[48:51], v[96:99], v[160:163], v[48:51]
	v_mfma_f32_16x16x32_bf16 v[36:39], v[84:87], v[168:171], v[36:39]
	v_mfma_f32_16x16x32_bf16 v[32:35], v[96:99], v[168:171], v[32:35]
	v_mfma_f32_16x16x32_bf16 v[20:23], v[84:87], v[176:179], v[20:23]
	v_mfma_f32_16x16x32_bf16 v[16:19], v[96:99], v[176:179], v[16:19]
	v_mfma_f32_16x16x32_bf16 v[4:7], v[84:87], v[184:187], v[4:7]
	v_mfma_f32_16x16x32_bf16 v[0:3], v[96:99], v[184:187], v[0:3]
	v_mfma_f32_16x16x32_bf16 v[52:55], v[88:91], v[164:167], v[52:55]
	v_mfma_f32_16x16x32_bf16 v[48:51], v[100:103], v[164:167], v[48:51]
	v_mfma_f32_16x16x32_bf16 v[36:39], v[88:91], v[172:175], v[36:39]
	v_mfma_f32_16x16x32_bf16 v[32:35], v[100:103], v[172:175], v[32:35]
	v_mfma_f32_16x16x32_bf16 v[20:23], v[88:91], v[180:183], v[20:23]
	v_mfma_f32_16x16x32_bf16 v[16:19], v[100:103], v[180:183], v[16:19]
	v_mfma_f32_16x16x32_bf16 v[4:7], v[88:91], v[204:207], v[4:7]
	v_mfma_f32_16x16x32_bf16 v[0:3], v[100:103], v[204:207], v[0:3]
	s_setprio 0
	s_barrier
	s_add_i32 s70, s70, 2
	s_add_u32 s49, s49, 0x100
	s_addc_u32 s69, s69, 0
	s_add_u32 s22, s22, 0x100
	s_addc_u32 s23, s23, 0
	s_cmp_gt_u32 s70, 13
	s_cbranch_scc0 .LBB0_348
	s_and_b64 vcc, exec, s[42:43]
	s_cbranch_vccz .LBB0_351
	s_barrier

.LBB0_508:
	s_add_u32 s22, s12, 0xfffc0080
	s_addc_u32 s23, s13, -1
	s_add_i32 s76, 0, 0x10000
	s_cmp_eq_u32 s86, 12
	s_cselect_b32 s51, s33, s23
	s_cselect_b32 s50, s39, s22
	s_cselect_b32 s23, s35, s85
	s_cselect_b32 s22, s41, s49
	s_add_i32 s77, 0, 0x14000
	v_add_u32_e32 v140, s76, v155
	v_add_u32_e32 v174, s77, v155
	ds_read_b128 v[128:131], v140
	ds_read_b128 v[132:135], v140 offset:1024
	ds_read_b128 v[136:139], v140 offset:2048
	ds_read_b128 v[140:143], v140 offset:3072
	ds_read_b128 v[162:165], v174
	ds_read_b128 v[166:169], v174 offset:1024
	ds_read_b128 v[170:173], v174 offset:2048
	ds_read_b128 v[174:177], v174 offset:3072
	v_lshl_add_u64 v[186:187], s[12:13], 0, v[160:161]
	s_add_i32 m0, s58, 0xc000
	ds_read_b128 v[178:181], v205
	ds_read_b128 v[182:185], v205 offset:1024
	ds_read_b128 v[194:197], v205 offset:2048
	ds_read_b128 v[198:201], v205 offset:3072
	ds_read_b128 v[206:209], v205 offset:4096
	ds_read_b128 v[210:213], v205 offset:5120
	ds_read_b128 v[214:217], v205 offset:6144
	ds_read_b128 v[218:221], v205 offset:7168
	global_load_lds_dwordx4 v[186:187], off
	v_lshl_add_u64 v[186:187], s[12:13], 0, v[158:159]
	s_add_i32 m0, s58, 0xe000
	s_nop 0
	global_load_lds_dwordx4 v[186:187], off
	s_waitcnt vmcnt(8)
	s_waitcnt lgkmcnt(0)
	s_barrier
	s_setprio 1
	s_waitcnt lgkmcnt(0)
	v_mfma_f32_16x16x32_bf16 v[124:127], v[128:131], v[178:181], v[124:127]
	v_mfma_f32_16x16x32_bf16 v[120:123], v[136:139], v[178:181], v[120:123]
	v_mfma_f32_16x16x32_bf16 v[108:111], v[128:131], v[194:197], v[108:111]
	v_mfma_f32_16x16x32_bf16 v[104:107], v[136:139], v[194:197], v[104:107]
	v_mfma_f32_16x16x32_bf16 v[92:95], v[128:131], v[206:209], v[92:95]
	v_mfma_f32_16x16x32_bf16 v[88:91], v[136:139], v[206:209], v[88:91]
	v_mfma_f32_16x16x32_bf16 v[76:79], v[128:131], v[214:217], v[76:79]
	v_mfma_f32_16x16x32_bf16 v[72:75], v[136:139], v[214:217], v[72:75]
	s_setprio 0
	s_setprio 1
	v_mfma_f32_16x16x32_bf16 v[124:127], v[132:135], v[182:185], v[124:127]
	v_mfma_f32_16x16x32_bf16 v[120:123], v[140:143], v[182:185], v[120:123]
	v_mfma_f32_16x16x32_bf16 v[108:111], v[132:135], v[198:201], v[108:111]
	v_mfma_f32_16x16x32_bf16 v[104:107], v[140:143], v[198:201], v[104:107]
	v_mfma_f32_16x16x32_bf16 v[92:95], v[132:135], v[210:213], v[92:95]
	v_mfma_f32_16x16x32_bf16 v[88:91], v[140:143], v[210:213], v[88:91]
	v_mfma_f32_16x16x32_bf16 v[76:79], v[132:135], v[218:221], v[76:79]
	v_mfma_f32_16x16x32_bf16 v[72:75], v[140:143], v[218:221], v[72:75]
	v_mfma_f32_16x16x32_bf16 v[116:119], v[162:165], v[178:181], v[116:119]
	v_mfma_f32_16x16x32_bf16 v[112:115], v[170:173], v[178:181], v[112:115]
	v_mfma_f32_16x16x32_bf16 v[100:103], v[162:165], v[194:197], v[100:103]
	v_mfma_f32_16x16x32_bf16 v[96:99], v[170:173], v[194:197], v[96:99]
	v_mfma_f32_16x16x32_bf16 v[84:87], v[162:165], v[206:209], v[84:87]
	v_mfma_f32_16x16x32_bf16 v[80:83], v[170:173], v[206:209], v[80:83]
	v_mfma_f32_16x16x32_bf16 v[68:71], v[162:165], v[214:217], v[68:71]
	v_mfma_f32_16x16x32_bf16 v[64:67], v[170:173], v[214:217], v[64:67]
	v_mfma_f32_16x16x32_bf16 v[116:119], v[166:169], v[182:185], v[116:119]
	v_mfma_f32_16x16x32_bf16 v[112:115], v[174:177], v[182:185], v[112:115]
	v_mfma_f32_16x16x32_bf16 v[100:103], v[166:169], v[198:201], v[100:103]
	v_mfma_f32_16x16x32_bf16 v[96:99], v[174:177], v[198:201], v[96:99]
	v_mfma_f32_16x16x32_bf16 v[84:87], v[166:169], v[210:213], v[84:87]
	v_mfma_f32_16x16x32_bf16 v[80:83], v[174:177], v[210:213], v[80:83]
	v_mfma_f32_16x16x32_bf16 v[68:71], v[166:169], v[218:221], v[68:71]
	v_mfma_f32_16x16x32_bf16 v[64:67], v[174:177], v[218:221], v[64:67]
	s_setprio 0
	s_barrier
	s_add_i32 s76, s76, s57
	v_lshl_add_u64 v[186:187], s[22:23], 0, v[146:147]
	s_mov_b32 m0, s76
	ds_read_b128 v[178:181], v205 offset:16384
	ds_read_b128 v[182:185], v205 offset:17408
	ds_read_b128 v[194:197], v205 offset:18432
	ds_read_b128 v[198:201], v205 offset:19456
	ds_read_b128 v[206:209], v205 offset:20480
	ds_read_b128 v[210:213], v205 offset:21504
	ds_read_b128 v[214:217], v205 offset:22528
	ds_read_b128 v[218:221], v205 offset:23552
	global_load_lds_dwordx4 v[186:187], off
	s_add_i32 m0, s76, 0x2000
	s_add_u32 s90, s22, 0x40000
	v_lshl_add_u64 v[222:223], s[22:23], 0, v[150:151]
	s_addc_u32 s91, s23, 0
	s_add_i32 s76, s77, s57
	global_load_lds_dwordx4 v[222:223], off
	v_lshl_add_u64 v[224:225], s[90:91], 0, v[146:147]
	s_mov_b32 m0, s76
	v_lshl_add_u64 v[226:227], s[50:51], 0, v[148:149]
	global_load_lds_dwordx4 v[224:225], off
	v_lshl_add_u64 v[224:225], s[90:91], 0, v[150:151]
	s_add_i32 m0, s76, 0x2000
	s_nop 0
	global_load_lds_dwordx4 v[224:225], off
	v_lshl_add_u64 v[224:225], s[50:51], 0, v[144:145]
	s_mov_b32 m0, s58
	s_nop 0
	global_load_lds_dwordx4 v[224:225], off
	s_mov_b32 m0, s59
	s_nop 0
	global_load_lds_dwordx4 v[226:227], off
	s_waitcnt vmcnt(8)
	s_waitcnt lgkmcnt(0)
	s_barrier
	s_setprio 1
	s_waitcnt lgkmcnt(0)
	v_mfma_f32_16x16x32_bf16 v[60:63], v[128:131], v[178:181], v[60:63]
	v_mfma_f32_16x16x32_bf16 v[56:59], v[136:139], v[178:181], v[56:59]
	v_mfma_f32_16x16x32_bf16 v[44:47], v[128:131], v[194:197], v[44:47]
	v_mfma_f32_16x16x32_bf16 v[40:43], v[136:139], v[194:197], v[40:43]
	v_mfma_f32_16x16x32_bf16 v[28:31], v[128:131], v[206:209], v[28:31]
	v_mfma_f32_16x16x32_bf16 v[24:27], v[136:139], v[206:209], v[24:27]
	v_mfma_f32_16x16x32_bf16 v[12:15], v[128:131], v[214:217], v[12:15]
	v_mfma_f32_16x16x32_bf16 v[8:11], v[136:139], v[214:217], v[8:11]
	s_setprio 0
	s_setprio 1
	v_mfma_f32_16x16x32_bf16 v[60:63], v[132:135], v[182:185], v[60:63]
	v_mfma_f32_16x16x32_bf16 v[56:59], v[140:143], v[182:185], v[56:59]
	v_mfma_f32_16x16x32_bf16 v[44:47], v[132:135], v[198:201], v[44:47]
	v_mfma_f32_16x16x32_bf16 v[40:43], v[140:143], v[198:201], v[40:43]
	v_mfma_f32_16x16x32_bf16 v[28:31], v[132:135], v[210:213], v[28:31]
	v_mfma_f32_16x16x32_bf16 v[24:27], v[140:143], v[210:213], v[24:27]
	v_mfma_f32_16x16x32_bf16 v[12:15], v[132:135], v[218:221], v[12:15]
	v_mfma_f32_16x16x32_bf16 v[8:11], v[140:143], v[218:221], v[8:11]
	v_mfma_f32_16x16x32_bf16 v[52:55], v[162:165], v[178:181], v[52:55]
	v_mfma_f32_16x16x32_bf16 v[48:51], v[170:173], v[178:181], v[48:51]
	v_mfma_f32_16x16x32_bf16 v[36:39], v[162:165], v[194:197], v[36:39]
	v_mfma_f32_16x16x32_bf16 v[32:35], v[170:173], v[194:197], v[32:35]
	v_mfma_f32_16x16x32_bf16 v[20:23], v[162:165], v[206:209], v[20:23]
	v_mfma_f32_16x16x32_bf16 v[16:19], v[170:173], v[206:209], v[16:19]
	v_mfma_f32_16x16x32_bf16 v[4:7], v[162:165], v[214:217], v[4:7]
	v_mfma_f32_16x16x32_bf16 v[0:3], v[170:173], v[214:217], v[0:3]
	v_mfma_f32_16x16x32_bf16 v[52:55], v[166:169], v[182:185], v[52:55]
	v_mfma_f32_16x16x32_bf16 v[48:51], v[174:177], v[182:185], v[48:51]
	v_mfma_f32_16x16x32_bf16 v[36:39], v[166:169], v[198:201], v[36:39]
	v_mfma_f32_16x16x32_bf16 v[32:35], v[174:177], v[198:201], v[32:35]
	v_mfma_f32_16x16x32_bf16 v[20:23], v[166:169], v[210:213], v[20:23]
	v_mfma_f32_16x16x32_bf16 v[16:19], v[174:177], v[210:213], v[16:19]
	v_mfma_f32_16x16x32_bf16 v[4:7], v[166:169], v[218:221], v[4:7]
	v_mfma_f32_16x16x32_bf16 v[0:3], v[174:177], v[218:221], v[0:3]
	s_setprio 0
	s_barrier
	s_add_i32 s76, 0, 0x18000
	s_add_i32 s77, 0, 0x1c000
	v_add_u32_e32 v140, s76, v155
	v_add_u32_e32 v174, s77, v155
	ds_read_b128 v[128:131], v140
	ds_read_b128 v[132:135], v140 offset:1024
	ds_read_b128 v[136:139], v140 offset:2048
	ds_read_b128 v[140:143], v140 offset:3072
	ds_read_b128 v[162:165], v174
	ds_read_b128 v[166:169], v174 offset:1024
	ds_read_b128 v[170:173], v174 offset:2048
	ds_read_b128 v[174:177], v174 offset:3072
	s_add_u32 s50, s50, 0x40000
	s_addc_u32 s51, s51, 0
	s_mov_b32 m0, s60
	v_lshl_add_u64 v[234:235], s[50:51], 0, v[144:145]
	ds_read_b128 v[178:181], v205 offset:32768
	ds_read_b128 v[182:185], v205 offset:33792
	ds_read_b128 v[194:197], v205 offset:34816
	ds_read_b128 v[198:201], v205 offset:35840
	ds_read_b128 v[206:209], v205 offset:36864
	ds_read_b128 v[210:213], v205 offset:37888
	ds_read_b128 v[214:217], v205 offset:38912
	ds_read_b128 v[218:221], v205 offset:39936
	global_load_lds_dwordx4 v[234:235], off
	v_lshl_add_u64 v[234:235], s[50:51], 0, v[148:149]
	s_mov_b32 m0, s61
	s_nop 0
	global_load_lds_dwordx4 v[234:235], off
	s_waitcnt vmcnt(8)
	s_waitcnt lgkmcnt(0)
	s_barrier
	s_setprio 1
	s_waitcnt lgkmcnt(0)
	v_mfma_f32_16x16x32_bf16 v[124:127], v[128:131], v[178:181], v[124:127]
	v_mfma_f32_16x16x32_bf16 v[120:123], v[136:139], v[178:181], v[120:123]
	v_mfma_f32_16x16x32_bf16 v[108:111], v[128:131], v[194:197], v[108:111]
	v_mfma_f32_16x16x32_bf16 v[104:107], v[136:139], v[194:197], v[104:107]
	v_mfma_f32_16x16x32_bf16 v[92:95], v[128:131], v[206:209], v[92:95]
	v_mfma_f32_16x16x32_bf16 v[88:91], v[136:139], v[206:209], v[88:91]
	v_mfma_f32_16x16x32_bf16 v[76:79], v[128:131], v[214:217], v[76:79]
	v_mfma_f32_16x16x32_bf16 v[72:75], v[136:139], v[214:217], v[72:75]
	s_setprio 0
	s_setprio 1
	v_mfma_f32_16x16x32_bf16 v[124:127], v[132:135], v[182:185], v[124:127]
	v_mfma_f32_16x16x32_bf16 v[120:123], v[140:143], v[182:185], v[120:123]
	v_mfma_f32_16x16x32_bf16 v[108:111], v[132:135], v[198:201], v[108:111]
	v_mfma_f32_16x16x32_bf16 v[104:107], v[140:143], v[198:201], v[104:107]
	v_mfma_f32_16x16x32_bf16 v[92:95], v[132:135], v[210:213], v[92:95]
	v_mfma_f32_16x16x32_bf16 v[88:91], v[140:143], v[210:213], v[88:91]
	v_mfma_f32_16x16x32_bf16 v[76:79], v[132:135], v[218:221], v[76:79]
	v_mfma_f32_16x16x32_bf16 v[72:75], v[140:143], v[218:221], v[72:75]
	v_mfma_f32_16x16x32_bf16 v[116:119], v[162:165], v[178:181], v[116:119]
	v_mfma_f32_16x16x32_bf16 v[112:115], v[170:173], v[178:181], v[112:115]
	v_mfma_f32_16x16x32_bf16 v[100:103], v[162:165], v[194:197], v[100:103]
	v_mfma_f32_16x16x32_bf16 v[96:99], v[170:173], v[194:197], v[96:99]
	v_mfma_f32_16x16x32_bf16 v[84:87], v[162:165], v[206:209], v[84:87]
	v_mfma_f32_16x16x32_bf16 v[80:83], v[170:173], v[206:209], v[80:83]
	v_mfma_f32_16x16x32_bf16 v[68:71], v[162:165], v[214:217], v[68:71]
	v_mfma_f32_16x16x32_bf16 v[64:67], v[170:173], v[214:217], v[64:67]
	v_mfma_f32_16x16x32_bf16 v[116:119], v[166:169], v[182:185], v[116:119]
	v_mfma_f32_16x16x32_bf16 v[112:115], v[174:177], v[182:185], v[112:115]
	v_mfma_f32_16x16x32_bf16 v[100:103], v[166:169], v[198:201], v[100:103]
	v_mfma_f32_16x16x32_bf16 v[96:99], v[174:177], v[198:201], v[96:99]
	v_mfma_f32_16x16x32_bf16 v[84:87], v[166:169], v[210:213], v[84:87]
	v_mfma_f32_16x16x32_bf16 v[80:83], v[174:177], v[210:213], v[80:83]
	v_mfma_f32_16x16x32_bf16 v[68:71], v[166:169], v[218:221], v[68:71]
	v_mfma_f32_16x16x32_bf16 v[64:67], v[174:177], v[218:221], v[64:67]
	s_setprio 0
	s_barrier
	s_add_i32 s50, s76, s57
	v_lshl_add_u64 v[186:187], v[186:187], 0, s[30:31]
	s_mov_b32 m0, s50
	ds_read_b128 v[178:181], v205 offset:49152
	ds_read_b128 v[182:185], v205 offset:50176
	ds_read_b128 v[194:197], v205 offset:51200
	ds_read_b128 v[198:201], v205 offset:52224
	ds_read_b128 v[206:209], v205 offset:53248
	ds_read_b128 v[210:213], v205 offset:54272
	ds_read_b128 v[214:217], v205 offset:55296
	ds_read_b128 v[218:221], v205 offset:56320
	global_load_lds_dwordx4 v[186:187], off
	s_add_i32 m0, s50, 0x2000
	s_add_u32 s22, s22, 0x40080
	v_lshl_add_u64 v[186:187], v[222:223], 0, s[30:31]
	s_addc_u32 s23, s23, 0
	s_add_i32 s50, s77, s57
	global_load_lds_dwordx4 v[186:187], off
	v_lshl_add_u64 v[186:187], s[22:23], 0, v[146:147]
	s_mov_b32 m0, s50
	s_nop 0
	global_load_lds_dwordx4 v[186:187], off
	v_lshl_add_u64 v[186:187], s[22:23], 0, v[150:151]
	s_add_i32 m0, s50, 0x2000
	s_nop 0
	global_load_lds_dwordx4 v[186:187], off
	v_lshl_add_u64 v[186:187], v[224:225], 0, s[30:31]
	s_mov_b32 m0, s65
	s_nop 0
	global_load_lds_dwordx4 v[186:187], off
	v_lshl_add_u64 v[186:187], v[226:227], 0, s[30:31]
	s_mov_b32 m0, s66
	s_nop 0
	global_load_lds_dwordx4 v[186:187], off
	s_waitcnt vmcnt(8)
	s_waitcnt lgkmcnt(0)
	s_barrier
	s_setprio 1
	s_waitcnt lgkmcnt(0)
	v_mfma_f32_16x16x32_bf16 v[60:63], v[128:131], v[178:181], v[60:63]
	v_mfma_f32_16x16x32_bf16 v[56:59], v[136:139], v[178:181], v[56:59]
	v_mfma_f32_16x16x32_bf16 v[44:47], v[128:131], v[194:197], v[44:47]
	v_mfma_f32_16x16x32_bf16 v[40:43], v[136:139], v[194:197], v[40:43]
	v_mfma_f32_16x16x32_bf16 v[28:31], v[128:131], v[206:209], v[28:31]
	v_mfma_f32_16x16x32_bf16 v[24:27], v[136:139], v[206:209], v[24:27]
	v_mfma_f32_16x16x32_bf16 v[12:15], v[128:131], v[214:217], v[12:15]
	v_mfma_f32_16x16x32_bf16 v[8:11], v[136:139], v[214:217], v[8:11]
	s_setprio 0
	s_setprio 1
	v_mfma_f32_16x16x32_bf16 v[60:63], v[132:135], v[182:185], v[60:63]
	v_mfma_f32_16x16x32_bf16 v[56:59], v[140:143], v[182:185], v[56:59]
	v_mfma_f32_16x16x32_bf16 v[44:47], v[132:135], v[198:201], v[44:47]
	v_mfma_f32_16x16x32_bf16 v[40:43], v[140:143], v[198:201], v[40:43]
	v_mfma_f32_16x16x32_bf16 v[28:31], v[132:135], v[210:213], v[28:31]
	v_mfma_f32_16x16x32_bf16 v[24:27], v[140:143], v[210:213], v[24:27]
	v_mfma_f32_16x16x32_bf16 v[12:15], v[132:135], v[218:221], v[12:15]
	v_mfma_f32_16x16x32_bf16 v[8:11], v[140:143], v[218:221], v[8:11]
	v_mfma_f32_16x16x32_bf16 v[52:55], v[162:165], v[178:181], v[52:55]
	v_mfma_f32_16x16x32_bf16 v[48:51], v[170:173], v[178:181], v[48:51]
	v_mfma_f32_16x16x32_bf16 v[36:39], v[162:165], v[194:197], v[36:39]
	v_mfma_f32_16x16x32_bf16 v[32:35], v[170:173], v[194:197], v[32:35]
	v_mfma_f32_16x16x32_bf16 v[20:23], v[162:165], v[206:209], v[20:23]
	v_mfma_f32_16x16x32_bf16 v[16:19], v[170:173], v[206:209], v[16:19]
	v_mfma_f32_16x16x32_bf16 v[4:7], v[162:165], v[214:217], v[4:7]
	v_mfma_f32_16x16x32_bf16 v[0:3], v[170:173], v[214:217], v[0:3]
	v_mfma_f32_16x16x32_bf16 v[52:55], v[166:169], v[182:185], v[52:55]
	v_mfma_f32_16x16x32_bf16 v[48:51], v[174:177], v[182:185], v[48:51]
	v_mfma_f32_16x16x32_bf16 v[36:39], v[166:169], v[198:201], v[36:39]
	v_mfma_f32_16x16x32_bf16 v[32:35], v[174:177], v[198:201], v[32:35]
	v_mfma_f32_16x16x32_bf16 v[20:23], v[166:169], v[210:213], v[20:23]
	v_mfma_f32_16x16x32_bf16 v[16:19], v[174:177], v[210:213], v[16:19]
	v_mfma_f32_16x16x32_bf16 v[4:7], v[166:169], v[218:221], v[4:7]
	v_mfma_f32_16x16x32_bf16 v[0:3], v[174:177], v[218:221], v[0:3]
	s_setprio 0
	s_barrier
	s_add_i32 s86, s86, 2
	s_add_u32 s49, s49, 0x100
	s_addc_u32 s85, s85, 0
	s_add_u32 s12, s12, 0x100
	s_addc_u32 s13, s13, 0
	s_cmp_gt_u32 s86, 13
	s_cbranch_scc0 .LBB0_508
	s_and_b64 vcc, exec, s[26:27]
	s_cbranch_vccz .LBB0_511
	s_barrier
